# mod_unit: cross-wave reduction reads batched 8 pairs per wait; final stage waits for the bias load once instead of draining each store (10x vmcnt(0)), on top of v7
# baseline (speedup 1.0000x reference)
.LBB0_683:
	s_cmp_gt_i32 s1, 3
	s_waitcnt lgkmcnt(0)
	s_barrier
	s_cbranch_scc1 .LBB0_685
	s_mul_i32 s0, s1, 0x5000
	s_add_i32 s0, s0, 0
	v_lshl_add_u32 v80, v235, 2, s0
	ds_read2st64_b32 v[216:217], v80 offset1:1
	ds_read2st64_b32 v[218:219], v80 offset0:2 offset1:3
	ds_read2st64_b32 v[220:221], v80 offset0:4 offset1:5
	ds_read2st64_b32 v[224:225], v80 offset0:6 offset1:7
	ds_read2st64_b32 v[240:241], v80 offset0:8 offset1:9
	ds_read2st64_b32 v[242:243], v80 offset0:10 offset1:11
	ds_read2st64_b32 v[244:245], v80 offset0:12 offset1:13
	ds_read2st64_b32 v[246:247], v80 offset0:14 offset1:15
	s_waitcnt lgkmcnt(0)
	v_add_f32_e32 v64, v64, v216
	v_add_f32_e32 v65, v65, v217
	v_add_f32_e32 v66, v66, v218
	v_add_f32_e32 v67, v67, v219
	v_add_f32_e32 v68, v68, v220
	v_add_f32_e32 v69, v69, v221
	v_add_f32_e32 v70, v70, v224
	v_add_f32_e32 v71, v71, v225
	v_add_f32_e32 v72, v72, v240
	v_add_f32_e32 v73, v73, v241
	v_add_f32_e32 v74, v74, v242
	v_add_f32_e32 v75, v75, v243
	v_add_f32_e32 v76, v76, v244
	v_add_f32_e32 v77, v77, v245
	v_add_f32_e32 v78, v78, v246
	v_add_f32_e32 v79, v79, v247
	ds_read2st64_b32 v[216:217], v80 offset0:16 offset1:17
	ds_read2st64_b32 v[218:219], v80 offset0:18 offset1:19
	ds_read2st64_b32 v[220:221], v80 offset0:20 offset1:21
	ds_read2st64_b32 v[224:225], v80 offset0:22 offset1:23
	ds_read2st64_b32 v[240:241], v80 offset0:24 offset1:25
	ds_read2st64_b32 v[242:243], v80 offset0:26 offset1:27
	ds_read2st64_b32 v[244:245], v80 offset0:28 offset1:29
	ds_read2st64_b32 v[246:247], v80 offset0:30 offset1:31
	s_waitcnt lgkmcnt(0)
	v_add_f32_e32 v48, v48, v216
	v_add_f32_e32 v49, v49, v217
	v_add_f32_e32 v50, v50, v218
	v_add_f32_e32 v51, v51, v219
	v_add_f32_e32 v52, v52, v220
	v_add_f32_e32 v53, v53, v221
	v_add_f32_e32 v54, v54, v224
	v_add_f32_e32 v55, v55, v225
	v_add_f32_e32 v81, v56, v240
	v_add_f32_e32 v82, v57, v241
	v_add_f32_e32 v58, v58, v242
	v_add_f32_e32 v59, v59, v243
	v_add_f32_e32 v60, v60, v244
	v_add_f32_e32 v61, v61, v245
	v_add_f32_e32 v62, v62, v246
	v_add_f32_e32 v63, v63, v247
	ds_read2st64_b32 v[216:217], v80 offset0:32 offset1:33
	ds_read2st64_b32 v[218:219], v80 offset0:34 offset1:35
	ds_read2st64_b32 v[220:221], v80 offset0:36 offset1:37
	ds_read2st64_b32 v[224:225], v80 offset0:38 offset1:39
	ds_read2st64_b32 v[240:241], v80 offset0:40 offset1:41
	ds_read2st64_b32 v[242:243], v80 offset0:42 offset1:43
	ds_read2st64_b32 v[244:245], v80 offset0:44 offset1:45
	ds_read2st64_b32 v[246:247], v80 offset0:46 offset1:47
	s_waitcnt lgkmcnt(0)
	v_add_f32_e32 v56, v32, v216
	v_add_f32_e32 v57, v33, v217
	v_add_f32_e32 v34, v34, v218
	v_add_f32_e32 v35, v35, v219
	v_add_f32_e32 v36, v36, v220
	v_add_f32_e32 v37, v37, v221
	v_add_f32_e32 v38, v38, v224
	v_add_f32_e32 v39, v39, v225
	v_add_f32_e32 v40, v40, v240
	v_add_f32_e32 v41, v41, v241
	v_add_f32_e32 v42, v42, v242
	v_add_f32_e32 v43, v43, v243
	v_add_f32_e32 v44, v44, v244
	v_add_f32_e32 v45, v45, v245
	v_add_f32_e32 v46, v46, v246
	v_add_f32_e32 v47, v47, v247
	ds_read2st64_b32 v[216:217], v80 offset0:48 offset1:49
	ds_read2st64_b32 v[218:219], v80 offset0:50 offset1:51
	ds_read2st64_b32 v[220:221], v80 offset0:52 offset1:53
	ds_read2st64_b32 v[224:225], v80 offset0:54 offset1:55
	ds_read2st64_b32 v[240:241], v80 offset0:56 offset1:57
	ds_read2st64_b32 v[242:243], v80 offset0:58 offset1:59
	ds_read2st64_b32 v[244:245], v80 offset0:60 offset1:61
	ds_read2st64_b32 v[246:247], v80 offset0:62 offset1:63
	s_waitcnt lgkmcnt(0)
	v_add_f32_e32 v32, v16, v216
	v_add_f32_e32 v33, v17, v217
	v_add_f32_e32 v18, v18, v218
	v_add_f32_e32 v19, v19, v219
	v_add_f32_e32 v20, v20, v220
	v_add_f32_e32 v21, v21, v221
	v_add_f32_e32 v22, v22, v224
	v_add_f32_e32 v23, v23, v225
	v_add_f32_e32 v24, v24, v240
	v_add_f32_e32 v25, v25, v241
	v_add_f32_e32 v26, v26, v242
	v_add_f32_e32 v27, v27, v243
	v_add_f32_e32 v28, v28, v244
	v_add_f32_e32 v29, v29, v245
	v_add_f32_e32 v30, v30, v246
	v_add_f32_e32 v31, v31, v247
	ds_read2st64_b32 v[216:217], v80 offset0:64 offset1:65
	ds_read2st64_b32 v[218:219], v80 offset0:66 offset1:67
	ds_read2st64_b32 v[220:221], v80 offset0:68 offset1:69
	ds_read2st64_b32 v[224:225], v80 offset0:70 offset1:71
	ds_read2st64_b32 v[240:241], v80 offset0:72 offset1:73
	ds_read2st64_b32 v[242:243], v80 offset0:74 offset1:75
	ds_read2st64_b32 v[244:245], v80 offset0:76 offset1:77
	ds_read2st64_b32 v[246:247], v80 offset0:78 offset1:79
	s_waitcnt lgkmcnt(0)
	v_add_f32_e32 v16, v0, v216
	v_add_f32_e32 v17, v1, v217
	v_add_f32_e32 v2, v2, v218
	v_add_f32_e32 v3, v3, v219
	v_add_f32_e32 v4, v4, v220
	v_add_f32_e32 v5, v5, v221
	v_add_f32_e32 v6, v6, v224
	v_add_f32_e32 v7, v7, v225
	v_add_f32_e32 v8, v8, v240
	v_add_f32_e32 v9, v9, v241
	v_add_f32_e32 v10, v10, v242
	v_add_f32_e32 v11, v11, v243
	v_add_f32_e32 v12, v12, v244
	v_add_f32_e32 v13, v13, v245
	v_add_f32_e32 v0, v14, v246
	v_add_f32_e32 v1, v15, v247
	ds_write2st64_b32 v80, v64, v65 offset1:1
	ds_write2st64_b32 v80, v66, v67 offset0:2 offset1:3
	ds_write2st64_b32 v80, v68, v69 offset0:4 offset1:5
	ds_write2st64_b32 v80, v70, v71 offset0:6 offset1:7
	ds_write2st64_b32 v80, v72, v73 offset0:8 offset1:9
	ds_write2st64_b32 v80, v74, v75 offset0:10 offset1:11
	ds_write2st64_b32 v80, v76, v77 offset0:12 offset1:13
	ds_write2st64_b32 v80, v78, v79 offset0:14 offset1:15
	ds_write2st64_b32 v80, v48, v49 offset0:16 offset1:17
	ds_write2st64_b32 v80, v50, v51 offset0:18 offset1:19
	ds_write2st64_b32 v80, v52, v53 offset0:20 offset1:21
	ds_write2st64_b32 v80, v54, v55 offset0:22 offset1:23
	ds_write2st64_b32 v80, v81, v82 offset0:24 offset1:25
	ds_write2st64_b32 v80, v58, v59 offset0:26 offset1:27
	ds_write2st64_b32 v80, v60, v61 offset0:28 offset1:29
	ds_write2st64_b32 v80, v62, v63 offset0:30 offset1:31
	ds_write2st64_b32 v80, v56, v57 offset0:32 offset1:33
	ds_write2st64_b32 v80, v34, v35 offset0:34 offset1:35
	ds_write2st64_b32 v80, v36, v37 offset0:36 offset1:37
	ds_write2st64_b32 v80, v38, v39 offset0:38 offset1:39
	ds_write2st64_b32 v80, v40, v41 offset0:40 offset1:41
	ds_write2st64_b32 v80, v42, v43 offset0:42 offset1:43
	ds_write2st64_b32 v80, v44, v45 offset0:44 offset1:45
	ds_write2st64_b32 v80, v46, v47 offset0:46 offset1:47
	ds_write2st64_b32 v80, v32, v33 offset0:48 offset1:49
	ds_write2st64_b32 v80, v18, v19 offset0:50 offset1:51
	ds_write2st64_b32 v80, v20, v21 offset0:52 offset1:53
	ds_write2st64_b32 v80, v22, v23 offset0:54 offset1:55
	ds_write2st64_b32 v80, v24, v25 offset0:56 offset1:57
	ds_write2st64_b32 v80, v26, v27 offset0:58 offset1:59
	ds_write2st64_b32 v80, v28, v29 offset0:60 offset1:61
	ds_write2st64_b32 v80, v30, v31 offset0:62 offset1:63
	ds_write2st64_b32 v80, v16, v17 offset0:64 offset1:65
	ds_write2st64_b32 v80, v2, v3 offset0:66 offset1:67
	ds_write2st64_b32 v80, v4, v5 offset0:68 offset1:69
	ds_write2st64_b32 v80, v6, v7 offset0:70 offset1:71
	ds_write2st64_b32 v80, v8, v9 offset0:72 offset1:73
	ds_write2st64_b32 v80, v10, v11 offset0:74 offset1:75
	ds_write2st64_b32 v80, v12, v13 offset0:76 offset1:77
	ds_write2st64_b32 v80, v0, v1 offset0:78 offset1:79
.LBB0_685:
	s_mul_i32 s1, s15, 0x318000
	v_readlane_b32 s10, v251, 57
	s_mul_hi_i32 s0, s15, 0x318000
	v_readlane_b32 s11, v251, 58
	s_add_u32 s7, s10, s1
	s_waitcnt lgkmcnt(0)
	s_barrier
	s_addc_u32 s10, s11, s0
	s_load_dwordx2 s[0:1], s[2:3], 0x50
	s_mul_i32 s2, s15, 0x1800
	s_add_i32 s2, s2, s6
	v_or_b32_e32 v0, s2, v160
	v_ashrrev_i32_e32 v1, 31, v0
	s_waitcnt lgkmcnt(0)
	v_lshl_add_u64 v[0:1], v[0:1], 2, s[0:1]
	global_load_dword v2, v[0:1], off
	s_add_u32 s0, s7, s8
	v_lshrrev_b32_e32 v6, 5, v214
	v_lshlrev_b32_e32 v3, 2, v161
	s_addc_u32 s1, s10, s9
	v_lshlrev_b32_e32 v208, 2, v160
	v_bfe_u32 v4, v214, 6, 2
	v_and_b32_e32 v6, 24, v6
	v_lshl_add_u64 v[0:1], s[0:1], 0, v[208:209]
	s_mov_b64 s[0:1], 0x200000
	v_ashrrev_i32_e32 v5, 10, v214
	v_or3_b32 v4, v6, v4, v3
	v_lshl_add_u64 v[0:1], v[0:1], 0, s[0:1]
	v_cmp_lt_i32_e32 vcc, 0, v5
	v_cmp_gt_u32_e64 s[0:1], 4, v4
	s_or_b64 s[2:3], vcc, s[0:1]
	s_waitcnt vmcnt(0)
	s_and_saveexec_b64 s[0:1], s[2:3]
	s_cbranch_execz .LBB0_687
	v_lshl_add_u32 v8, v214, 2, 0
	ds_read2st64_b32 v[6:7], v8 offset1:80
	ds_read2st64_b32 v[8:9], v8 offset0:160 offset1:240
	v_lshl_add_u32 v5, v5, 5, v231
	v_cmp_lt_u32_e32 vcc, s59, v214
	s_nop 1
	v_cndmask_b32_e32 v5, 0, v5, vcc
	v_add_u32_e32 v10, v4, v5
	s_waitcnt lgkmcnt(1)
	v_mov_b32_e32 v4, v6
	s_waitcnt lgkmcnt(0)
	v_mov_b32_e32 v5, v8
	v_mov_b32_e32 v8, v7
	v_pk_add_f32 v[4:5], v[4:5], v[8:9]
	s_nop 0
	v_add_f32_e32 v4, v4, v5
	v_add_f32_e32 v6, v2, v4
	v_mad_i64_i32 v[4:5], s[2:3], v10, s33, v[0:1]
	global_store_dword v[4:5], v6, off
.LBB0_687:
	s_or_b64 exec, exec, s[0:1]
	v_add_u32_e32 v4, 0x200, v214
	v_lshrrev_b32_e32 v7, 5, v4
	v_bfe_u32 v6, v4, 6, 2
	v_and_b32_e32 v7, 24, v7
	v_ashrrev_i32_e32 v5, 10, v4
	v_or3_b32 v6, v6, v7, v3
	v_cmp_lt_i32_e32 vcc, 0, v5
	v_cmp_gt_u32_e64 s[0:1], 4, v6
	s_or_b64 s[2:3], vcc, s[0:1]
	s_and_saveexec_b64 s[0:1], s[2:3]
	s_cbranch_execz .LBB0_689
	v_lshl_add_u32 v5, v5, 5, v231
	v_cmp_lt_u32_e32 vcc, s59, v4
	s_nop 1
	v_cndmask_b32_e32 v4, 0, v5, vcc
	v_add_u32_e32 v10, v6, v4
	v_lshl_add_u32 v6, v214, 2, 0
	ds_read2st64_b32 v[4:5], v6 offset0:8 offset1:88
	ds_read2st64_b32 v[6:7], v6 offset0:168 offset1:248
	s_waitcnt lgkmcnt(1)
	v_mov_b32_e32 v8, v4
	s_waitcnt lgkmcnt(0)
	v_mov_b32_e32 v9, v6
	v_mov_b32_e32 v6, v5
	v_pk_add_f32 v[4:5], v[8:9], v[6:7]
	s_nop 0
	v_add_f32_e32 v4, v4, v5
	v_add_f32_e32 v6, v2, v4
	v_mad_i64_i32 v[4:5], s[2:3], v10, s33, v[0:1]
	global_store_dword v[4:5], v6, off
.LBB0_689:
	s_or_b64 exec, exec, s[0:1]
	v_add_u32_e32 v4, 0x400, v214
	v_ashrrev_i32_e32 v5, 10, v4
	v_bfe_u32 v6, v4, 6, 2
	v_lshrrev_b32_e32 v4, 5, v4
	v_and_b32_e32 v4, 24, v4
	v_or3_b32 v4, v6, v4, v3
	v_cmp_lt_i32_e32 vcc, 0, v5
	v_cmp_gt_u32_e64 s[0:1], 4, v4
	s_or_b64 s[2:3], vcc, s[0:1]
	s_and_saveexec_b64 s[0:1], s[2:3]
	s_cbranch_execz .LBB0_691
	v_lshl_add_u32 v8, v5, 5, v231
	v_lshl_add_u32 v5, v214, 2, 0
	v_add_u32_e32 v9, 0x1000, v5
	ds_read2st64_b32 v[6:7], v5 offset0:16 offset1:96
	ds_read_b32 v5, v5 offset:45056
	ds_read_b32 v9, v9 offset:61440
	s_movk_i32 s2, 0xfc00
	v_cmp_gt_u32_e32 vcc, s2, v214
	s_nop 1
	v_cndmask_b32_e32 v8, 0, v8, vcc
	v_add_u32_e32 v10, v4, v8
	s_waitcnt lgkmcnt(2)
	v_mov_b32_e32 v4, v6
	v_mov_b32_e32 v8, v7
	s_waitcnt lgkmcnt(0)
	v_pk_add_f32 v[4:5], v[4:5], v[8:9]
	s_nop 0
	v_add_f32_e32 v4, v4, v5
	v_add_f32_e32 v6, v2, v4
	v_mad_i64_i32 v[4:5], s[2:3], v10, s33, v[0:1]
	global_store_dword v[4:5], v6, off
.LBB0_691:
	s_or_b64 exec, exec, s[0:1]
	v_add_u32_e32 v4, 0x600, v214
	v_lshrrev_b32_e32 v7, 5, v4
	v_bfe_u32 v6, v4, 6, 2
	v_and_b32_e32 v7, 24, v7
	v_ashrrev_i32_e32 v5, 10, v4
	v_or3_b32 v6, v6, v7, v3
	v_cmp_lt_i32_e32 vcc, 0, v5
	v_cmp_gt_u32_e64 s[0:1], 4, v6
	s_or_b64 s[2:3], vcc, s[0:1]
	s_and_saveexec_b64 s[0:1], s[2:3]
	s_cbranch_execz .LBB0_693
	v_lshl_add_u32 v5, v5, 5, v231
	v_cmp_lt_u32_e32 vcc, s59, v4
	s_nop 1
	v_cndmask_b32_e32 v4, 0, v5, vcc
	v_add_u32_e32 v10, v6, v4
	v_lshl_add_u32 v6, v214, 2, 0
	v_add_u32_e32 v8, 0x1800, v6
	ds_read2st64_b32 v[4:5], v6 offset0:24 offset1:104
	ds_read_b32 v7, v6 offset:47104
	ds_read_b32 v9, v8 offset:61440
	s_waitcnt lgkmcnt(2)
	v_mov_b32_e32 v6, v4
	v_mov_b32_e32 v8, v5
	s_waitcnt lgkmcnt(0)
	v_pk_add_f32 v[4:5], v[6:7], v[8:9]
	s_nop 0
	v_add_f32_e32 v4, v4, v5
	v_add_f32_e32 v6, v2, v4
	v_mad_i64_i32 v[4:5], s[2:3], v10, s33, v[0:1]
	global_store_dword v[4:5], v6, off
.LBB0_693:
	s_or_b64 exec, exec, s[0:1]
	v_add_u32_e32 v4, 0x800, v214
	v_lshrrev_b32_e32 v7, 5, v4
	v_bfe_u32 v6, v4, 6, 2
	v_and_b32_e32 v7, 24, v7
	v_ashrrev_i32_e32 v5, 10, v4
	v_or3_b32 v6, v6, v7, v3
	v_cmp_lt_i32_e32 vcc, 0, v5
	v_cmp_gt_u32_e64 s[0:1], 4, v6
	s_or_b64 s[2:3], vcc, s[0:1]
	s_and_saveexec_b64 s[0:1], s[2:3]
	s_cbranch_execz .LBB0_695
	v_lshl_add_u32 v5, v5, 5, v231
	v_cmp_lt_u32_e32 vcc, s59, v4
	s_nop 1
	v_cndmask_b32_e32 v4, 0, v5, vcc
	v_add_u32_e32 v10, v6, v4
	v_lshl_add_u32 v6, v214, 2, 0
	v_add_u32_e32 v8, 0x2000, v6
	ds_read2st64_b32 v[4:5], v6 offset0:32 offset1:112
	ds_read_b32 v7, v6 offset:49152
	ds_read_b32 v9, v8 offset:61440
	s_waitcnt lgkmcnt(2)
	v_mov_b32_e32 v6, v4
	v_mov_b32_e32 v8, v5
	s_waitcnt lgkmcnt(0)
	v_pk_add_f32 v[4:5], v[6:7], v[8:9]
	s_nop 0
	v_add_f32_e32 v4, v4, v5
	v_add_f32_e32 v6, v2, v4
	v_mad_i64_i32 v[4:5], s[2:3], v10, s33, v[0:1]
	global_store_dword v[4:5], v6, off
.LBB0_695:
	s_or_b64 exec, exec, s[0:1]
	v_add_u32_e32 v4, 0xa00, v214
	v_lshrrev_b32_e32 v7, 5, v4
	v_bfe_u32 v6, v4, 6, 2
	v_and_b32_e32 v7, 24, v7
	v_ashrrev_i32_e32 v5, 10, v4
	v_or3_b32 v6, v6, v7, v3
	v_cmp_lt_i32_e32 vcc, 0, v5
	v_cmp_gt_u32_e64 s[0:1], 4, v6
	s_or_b64 s[2:3], vcc, s[0:1]
	s_and_saveexec_b64 s[0:1], s[2:3]
	s_cbranch_execz .LBB0_697
	v_lshl_add_u32 v5, v5, 5, v231
	v_cmp_lt_u32_e32 vcc, s59, v4
	s_nop 1
	v_cndmask_b32_e32 v4, 0, v5, vcc
	v_add_u32_e32 v10, v6, v4
	v_lshl_add_u32 v6, v214, 2, 0
	v_add_u32_e32 v8, 0x2800, v6
	ds_read2st64_b32 v[4:5], v6 offset0:40 offset1:120
	ds_read_b32 v7, v6 offset:51200
	ds_read_b32 v9, v8 offset:61440
	s_waitcnt lgkmcnt(2)
	v_mov_b32_e32 v6, v4
	v_mov_b32_e32 v8, v5
	s_waitcnt lgkmcnt(0)
	v_pk_add_f32 v[4:5], v[6:7], v[8:9]
	s_nop 0
	v_add_f32_e32 v4, v4, v5
	v_add_f32_e32 v6, v2, v4
	v_mad_i64_i32 v[4:5], s[2:3], v10, s33, v[0:1]
	global_store_dword v[4:5], v6, off
.LBB0_697:
	s_or_b64 exec, exec, s[0:1]
	v_add_u32_e32 v4, 0xc00, v214
	v_lshrrev_b32_e32 v7, 5, v4
	v_bfe_u32 v6, v4, 6, 2
	v_and_b32_e32 v7, 24, v7
	v_ashrrev_i32_e32 v5, 10, v4
	v_or3_b32 v6, v6, v7, v3
	v_cmp_lt_i32_e32 vcc, 0, v5
	v_cmp_gt_u32_e64 s[0:1], 4, v6
	s_or_b64 s[2:3], vcc, s[0:1]
	s_and_saveexec_b64 s[0:1], s[2:3]
	s_cbranch_execz .LBB0_699
	v_lshl_add_u32 v5, v5, 5, v231
	v_cmp_lt_u32_e32 vcc, s59, v4
	s_nop 1
	v_cndmask_b32_e32 v4, 0, v5, vcc
	v_add_u32_e32 v10, v6, v4
	v_lshl_add_u32 v6, v214, 2, 0
	v_add_u32_e32 v8, 0x3000, v6
	ds_read2st64_b32 v[4:5], v6 offset0:48 offset1:128
	ds_read_b32 v7, v6 offset:53248
	ds_read_b32 v9, v8 offset:61440
	s_waitcnt lgkmcnt(2)
	v_mov_b32_e32 v6, v4
	v_mov_b32_e32 v8, v5
	s_waitcnt lgkmcnt(0)
	v_pk_add_f32 v[4:5], v[6:7], v[8:9]
	s_nop 0
	v_add_f32_e32 v4, v4, v5
	v_add_f32_e32 v6, v2, v4
	v_mad_i64_i32 v[4:5], s[2:3], v10, s33, v[0:1]
	global_store_dword v[4:5], v6, off
.LBB0_699:
	s_or_b64 exec, exec, s[0:1]
	v_add_u32_e32 v4, 0xe00, v214
	v_lshrrev_b32_e32 v7, 5, v4
	v_bfe_u32 v6, v4, 6, 2
	v_and_b32_e32 v7, 24, v7
	v_ashrrev_i32_e32 v5, 10, v4
	v_or3_b32 v6, v6, v7, v3
	v_cmp_lt_i32_e32 vcc, 0, v5
	v_cmp_gt_u32_e64 s[0:1], 4, v6
	s_or_b64 s[2:3], vcc, s[0:1]
	s_and_saveexec_b64 s[0:1], s[2:3]
	s_cbranch_execz .LBB0_701
	v_lshl_add_u32 v5, v5, 5, v231
	v_cmp_lt_u32_e32 vcc, s59, v4
	s_nop 1
	v_cndmask_b32_e32 v4, 0, v5, vcc
	v_add_u32_e32 v10, v6, v4
	v_lshl_add_u32 v6, v214, 2, 0
	v_add_u32_e32 v8, 0x3800, v6
	ds_read2st64_b32 v[4:5], v6 offset0:56 offset1:136
	ds_read_b32 v7, v6 offset:55296
	ds_read_b32 v9, v8 offset:61440
	s_waitcnt lgkmcnt(2)
	v_mov_b32_e32 v6, v4
	v_mov_b32_e32 v8, v5
	s_waitcnt lgkmcnt(0)
	v_pk_add_f32 v[4:5], v[6:7], v[8:9]
	s_nop 0
	v_add_f32_e32 v4, v4, v5
	v_add_f32_e32 v6, v2, v4
	v_mad_i64_i32 v[4:5], s[2:3], v10, s33, v[0:1]
	global_store_dword v[4:5], v6, off
.LBB0_701:
	s_or_b64 exec, exec, s[0:1]
	v_add_u32_e32 v4, 0x1000, v214
	v_lshrrev_b32_e32 v7, 5, v4
	v_bfe_u32 v6, v4, 6, 2
	v_and_b32_e32 v7, 24, v7
	v_ashrrev_i32_e32 v5, 10, v4
	v_or3_b32 v6, v6, v7, v3
	v_cmp_lt_i32_e32 vcc, 0, v5
	v_cmp_gt_u32_e64 s[0:1], 4, v6
	s_or_b64 s[2:3], vcc, s[0:1]
	s_and_saveexec_b64 s[0:1], s[2:3]
	s_cbranch_execz .LBB0_703
	v_lshl_add_u32 v5, v5, 5, v231
	v_cmp_lt_u32_e32 vcc, s59, v4
	s_nop 1
	v_cndmask_b32_e32 v4, 0, v5, vcc
	v_add_u32_e32 v10, v6, v4
	v_lshl_add_u32 v6, v214, 2, 0
	v_add_u32_e32 v8, 0x4000, v6
	ds_read2st64_b32 v[4:5], v6 offset0:64 offset1:144
	ds_read_b32 v7, v6 offset:57344
	ds_read_b32 v9, v8 offset:61440
	s_waitcnt lgkmcnt(2)
	v_mov_b32_e32 v6, v4
	v_mov_b32_e32 v8, v5
	s_waitcnt lgkmcnt(0)
	v_pk_add_f32 v[4:5], v[6:7], v[8:9]
	s_nop 0
	v_add_f32_e32 v4, v4, v5
	v_add_f32_e32 v6, v2, v4
	v_mad_i64_i32 v[4:5], s[2:3], v10, s33, v[0:1]
	global_store_dword v[4:5], v6, off
.LBB0_703:
	s_or_b64 exec, exec, s[0:1]
	v_add_u32_e32 v4, 0x1200, v214
	v_lshrrev_b32_e32 v7, 5, v4
	v_bfe_u32 v6, v4, 6, 2
	v_and_b32_e32 v7, 24, v7
	v_ashrrev_i32_e32 v5, 10, v4
	v_or3_b32 v3, v6, v7, v3
	v_cmp_lt_i32_e32 vcc, 0, v5
	v_cmp_gt_u32_e64 s[0:1], 4, v3
	s_or_b64 s[2:3], vcc, s[0:1]
	s_and_saveexec_b64 s[0:1], s[2:3]
	s_cbranch_execz .LBB0_705
	v_lshl_add_u32 v5, v5, 5, v231
	v_cmp_lt_u32_e32 vcc, s59, v4
	v_lshl_add_u32 v6, v214, 2, 0
	v_add_u32_e32 v8, 0x4800, v6
	v_cndmask_b32_e32 v4, 0, v5, vcc
	v_add_u32_e32 v3, v3, v4
	ds_read2st64_b32 v[4:5], v6 offset0:72 offset1:152
	ds_read_b32 v7, v6 offset:59392
	ds_read_b32 v9, v8 offset:61440
	v_mad_i64_i32 v[0:1], s[2:3], v3, s33, v[0:1]
	s_waitcnt lgkmcnt(2)
	v_mov_b32_e32 v6, v4
	v_mov_b32_e32 v8, v5
	s_waitcnt lgkmcnt(0)
	v_pk_add_f32 v[4:5], v[6:7], v[8:9]
	s_nop 0
	v_add_f32_e32 v4, v4, v5
	v_add_f32_e32 v2, v2, v4
	global_store_dword v[0:1], v2, off

.LBB0_833:
	s_mul_i32 s1, s14, 0x318000
	v_readlane_b32 s10, v251, 57
	s_mul_hi_i32 s0, s14, 0x318000
	v_readlane_b32 s11, v251, 58
	s_add_u32 s5, s10, s1
	s_waitcnt lgkmcnt(0)
	s_barrier
	s_addc_u32 s10, s11, s0
	s_load_dwordx2 s[0:1], s[2:3], 0x50
	s_mul_i32 s2, s14, 0x1800
	s_add_i32 s2, s2, s4
	v_or_b32_e32 v0, s2, v160
	v_ashrrev_i32_e32 v1, 31, v0
	s_waitcnt lgkmcnt(0)
	v_lshl_add_u64 v[0:1], v[0:1], 2, s[0:1]
	global_load_dword v2, v[0:1], off
	s_add_u32 s0, s5, s6
	v_lshrrev_b32_e32 v6, 5, v214
	v_lshlrev_b32_e32 v3, 2, v161
	s_addc_u32 s1, s10, s7
	v_lshlrev_b32_e32 v208, 2, v160
	v_bfe_u32 v4, v214, 6, 2
	v_and_b32_e32 v6, 24, v6
	v_lshl_add_u64 v[0:1], s[0:1], 0, v[208:209]
	s_mov_b64 s[0:1], 0x200000
	v_ashrrev_i32_e32 v5, 10, v214
	v_or3_b32 v4, v6, v4, v3
	v_lshl_add_u64 v[0:1], v[0:1], 0, s[0:1]
	v_cmp_lt_i32_e32 vcc, 0, v5
	v_cmp_gt_u32_e64 s[0:1], 4, v4
	s_or_b64 s[2:3], vcc, s[0:1]
	s_waitcnt vmcnt(0)
	s_and_saveexec_b64 s[0:1], s[2:3]
	s_cbranch_execz .LBB0_835
	v_lshl_add_u32 v8, v214, 2, 0
	ds_read2st64_b32 v[6:7], v8 offset1:80
	ds_read2st64_b32 v[8:9], v8 offset0:160 offset1:240
	v_lshl_add_u32 v5, v5, 5, v231
	v_cmp_lt_u32_e32 vcc, s59, v214
	s_nop 1
	v_cndmask_b32_e32 v5, 0, v5, vcc
	v_add_u32_e32 v10, v4, v5
	s_waitcnt lgkmcnt(1)
	v_mov_b32_e32 v4, v6
	s_waitcnt lgkmcnt(0)
	v_mov_b32_e32 v5, v8
	v_mov_b32_e32 v8, v7
	v_pk_add_f32 v[4:5], v[4:5], v[8:9]
	s_nop 0
	v_add_f32_e32 v4, v4, v5
	v_add_f32_e32 v6, v2, v4
	v_mad_i64_i32 v[4:5], s[2:3], v10, s33, v[0:1]
	global_store_dword v[4:5], v6, off

.LBB0_873:
	s_mul_i32 s40, s50, 0x318000
	s_mul_hi_i32 s37, s50, 0x318000
	s_add_u32 s40, s47, s40
	s_mul_i32 s41, s50, 0x1800
	s_addc_u32 s37, s48, s37
	s_add_i32 s41, s41, s36
	v_or_b32_e32 v0, s41, v160
	v_ashrrev_i32_e32 v1, 31, v0
	v_lshl_add_u64 v[0:1], v[0:1], 2, s[6:7]
	s_waitcnt lgkmcnt(0)
	s_barrier
	global_load_dword v2, v[0:1], off
	s_add_u32 s36, s40, s38
	s_addc_u32 s37, s37, s39
	v_lshl_add_u64 v[0:1], s[36:37], 0, v[208:209]
	s_waitcnt vmcnt(0)
	s_and_saveexec_b64 s[36:37], s[14:15]
	s_cbranch_execz .LBB0_875
	ds_read2st64_b32 v[4:5], v194 offset1:80
	ds_read2st64_b32 v[6:7], v194 offset0:160 offset1:240
	s_waitcnt lgkmcnt(1)
	v_mov_b32_e32 v8, v4
	s_waitcnt lgkmcnt(0)
	v_mov_b32_e32 v9, v6
	v_mov_b32_e32 v6, v5
	v_pk_add_f32 v[4:5], v[8:9], v[6:7]
	s_nop 0
	v_add_f32_e32 v3, v4, v5
	v_add_f32_e32 v3, v2, v3
	v_lshl_add_u64 v[4:5], v[0:1], 0, v[166:167]
	global_store_dword v[4:5], v3, off
.LBB0_875:
	s_or_b64 exec, exec, s[36:37]
	s_and_saveexec_b64 s[36:37], s[16:17]
	s_movk_i32 s50, 0x4000
	v_readlane_b32 s41, v251, 62
	s_cbranch_execz .LBB0_884
	ds_read2st64_b32 v[4:5], v194 offset0:8 offset1:88
	ds_read2st64_b32 v[6:7], v194 offset0:168 offset1:248
	s_waitcnt lgkmcnt(1)
	v_mov_b32_e32 v8, v4
	s_waitcnt lgkmcnt(0)
	v_mov_b32_e32 v9, v6
	v_mov_b32_e32 v6, v5
	v_pk_add_f32 v[4:5], v[8:9], v[6:7]
	s_nop 0
	v_add_f32_e32 v3, v4, v5
	v_add_f32_e32 v3, v2, v3
	v_lshl_add_u64 v[4:5], v[0:1], 0, v[168:169]
	global_store_dword v[4:5], v3, off
	s_or_b64 exec, exec, s[36:37]
	s_and_saveexec_b64 s[36:37], s[18:19]
	s_cbranch_execnz .LBB0_885

.LBB0_878:
	v_add_u32_e32 v3, 0x1800, v194
	ds_read2st64_b32 v[4:5], v194 offset0:24 offset1:104
	ds_read_b32 v7, v194 offset:47104
	ds_read_b32 v9, v3 offset:61440
	s_waitcnt lgkmcnt(2)
	v_mov_b32_e32 v6, v4
	v_mov_b32_e32 v8, v5
	s_waitcnt lgkmcnt(0)
	v_pk_add_f32 v[4:5], v[6:7], v[8:9]
	s_nop 0
	v_add_f32_e32 v3, v4, v5
	v_add_f32_e32 v3, v2, v3
	v_lshl_add_u64 v[4:5], v[0:1], 0, v[172:173]
	global_store_dword v[4:5], v3, off
	s_or_b64 exec, exec, s[36:37]
	s_and_saveexec_b64 s[36:37], s[22:23]
	s_cbranch_execnz .LBB0_887

.LBB0_880:
	v_add_u32_e32 v3, 0x2800, v194
	ds_read2st64_b32 v[4:5], v194 offset0:40 offset1:120
	ds_read_b32 v7, v194 offset:51200
	ds_read_b32 v9, v3 offset:61440
	s_waitcnt lgkmcnt(2)
	v_mov_b32_e32 v6, v4
	v_mov_b32_e32 v8, v5
	s_waitcnt lgkmcnt(0)
	v_pk_add_f32 v[4:5], v[6:7], v[8:9]
	s_nop 0
	v_add_f32_e32 v3, v4, v5
	v_add_f32_e32 v3, v2, v3
	v_lshl_add_u64 v[4:5], v[0:1], 0, v[176:177]
	global_store_dword v[4:5], v3, off
	s_or_b64 exec, exec, s[36:37]
	s_and_saveexec_b64 s[36:37], s[28:29]
	s_cbranch_execnz .LBB0_889

.LBB0_882:
	ds_read2st64_b32 v[4:5], v194 offset0:56 offset1:136
	ds_read_b32 v7, v194 offset:55296
	ds_read_b32 v9, v195 offset:61440
	s_waitcnt lgkmcnt(2)
	v_mov_b32_e32 v6, v4
	v_mov_b32_e32 v8, v5
	s_waitcnt lgkmcnt(0)
	v_pk_add_f32 v[4:5], v[6:7], v[8:9]
	s_nop 0
	v_add_f32_e32 v3, v4, v5
	v_add_f32_e32 v3, v2, v3
	v_lshl_add_u64 v[4:5], v[0:1], 0, v[180:181]
	global_store_dword v[4:5], v3, off
	s_or_b64 exec, exec, s[36:37]
	s_and_saveexec_b64 s[36:37], s[34:35]
	s_cbranch_execnz .LBB0_891

.LBB0_885:
	v_add_u32_e32 v3, 0x1000, v194
	ds_read2st64_b32 v[4:5], v194 offset0:16 offset1:96
	ds_read_b32 v7, v194 offset:45056
	ds_read_b32 v9, v3 offset:61440
	s_waitcnt lgkmcnt(2)
	v_mov_b32_e32 v6, v4
	v_mov_b32_e32 v8, v5
	s_waitcnt lgkmcnt(0)
	v_pk_add_f32 v[4:5], v[6:7], v[8:9]
	s_nop 0
	v_add_f32_e32 v3, v4, v5
	v_add_f32_e32 v3, v2, v3
	v_lshl_add_u64 v[4:5], v[0:1], 0, v[170:171]
	global_store_dword v[4:5], v3, off
	s_or_b64 exec, exec, s[36:37]
	s_and_saveexec_b64 s[36:37], s[20:21]
	s_cbranch_execnz .LBB0_878

.LBB0_887:
	v_add_u32_e32 v3, 0x2000, v194
	ds_read2st64_b32 v[4:5], v194 offset0:32 offset1:112
	ds_read_b32 v7, v194 offset:49152
	ds_read_b32 v9, v3 offset:61440
	s_waitcnt lgkmcnt(2)
	v_mov_b32_e32 v6, v4
	v_mov_b32_e32 v8, v5
	s_waitcnt lgkmcnt(0)
	v_pk_add_f32 v[4:5], v[6:7], v[8:9]
	s_nop 0
	v_add_f32_e32 v3, v4, v5
	v_add_f32_e32 v3, v2, v3
	v_lshl_add_u64 v[4:5], v[0:1], 0, v[174:175]
	global_store_dword v[4:5], v3, off
	s_or_b64 exec, exec, s[36:37]
	s_and_saveexec_b64 s[36:37], s[26:27]
	s_cbranch_execnz .LBB0_880

.LBB0_889:
	v_add_u32_e32 v3, 0x3000, v194
	ds_read2st64_b32 v[4:5], v194 offset0:48 offset1:128
	ds_read_b32 v7, v194 offset:53248
	ds_read_b32 v9, v3 offset:61440
	s_waitcnt lgkmcnt(2)
	v_mov_b32_e32 v6, v4
	v_mov_b32_e32 v8, v5
	s_waitcnt lgkmcnt(0)
	v_pk_add_f32 v[4:5], v[6:7], v[8:9]
	s_nop 0
	v_add_f32_e32 v3, v4, v5
	v_add_f32_e32 v3, v2, v3
	v_lshl_add_u64 v[4:5], v[0:1], 0, v[178:179]
	global_store_dword v[4:5], v3, off
	s_or_b64 exec, exec, s[36:37]
	s_and_saveexec_b64 s[36:37], s[30:31]
	s_cbranch_execnz .LBB0_882

.LBB0_891:
	ds_read2st64_b32 v[4:5], v194 offset0:64 offset1:144
	ds_read_b32 v7, v194 offset:57344
	ds_read_b32 v9, v196 offset:61440
	s_waitcnt lgkmcnt(2)
	v_mov_b32_e32 v6, v4
	v_mov_b32_e32 v8, v5
	s_waitcnt lgkmcnt(0)
	v_pk_add_f32 v[4:5], v[6:7], v[8:9]
	s_nop 0
	v_add_f32_e32 v3, v4, v5
	v_add_f32_e32 v3, v2, v3
	v_lshl_add_u64 v[4:5], v[0:1], 0, v[182:183]
	global_store_dword v[4:5], v3, off
	s_or_b64 exec, exec, s[36:37]
	s_and_saveexec_b64 s[36:37], s[2:3]
	s_cbranch_execz .LBB0_858
.LBB0_892:
	ds_read2st64_b32 v[4:5], v194 offset0:72 offset1:152
	ds_read_b32 v7, v194 offset:59392
	ds_read_b32 v9, v197 offset:61440
	v_lshl_add_u64 v[0:1], v[0:1], 0, v[184:185]
	s_waitcnt lgkmcnt(2)
	v_mov_b32_e32 v6, v4
	v_mov_b32_e32 v8, v5
	s_waitcnt lgkmcnt(0)
	v_pk_add_f32 v[4:5], v[6:7], v[8:9]
	s_nop 0
	v_add_f32_e32 v3, v4, v5
	v_add_f32_e32 v2, v2, v3
	global_store_dword v[0:1], v2, off
	s_branch .LBB0_858

.LBB0_912:
	s_mul_i32 s40, s52, 0x318000
	s_mul_hi_i32 s37, s52, 0x318000
	s_add_u32 s40, s50, s40
	s_mul_i32 s41, s52, 0x1800
	s_addc_u32 s37, s51, s37
	s_add_i32 s41, s41, s36
	v_or_b32_e32 v0, s41, v160
	v_ashrrev_i32_e32 v1, 31, v0
	v_lshl_add_u64 v[0:1], v[0:1], 2, s[6:7]
	s_waitcnt lgkmcnt(0)
	s_barrier
	global_load_dword v2, v[0:1], off
	s_add_u32 s36, s40, s38
	s_addc_u32 s37, s37, s39
	v_lshl_add_u64 v[0:1], s[36:37], 0, v[208:209]
	s_waitcnt vmcnt(0)
	s_and_saveexec_b64 s[36:37], s[14:15]
	s_cbranch_execz .LBB0_914
	ds_read2st64_b32 v[4:5], v194 offset1:80
	ds_read2st64_b32 v[6:7], v194 offset0:160 offset1:240
	s_waitcnt lgkmcnt(1)
	v_mov_b32_e32 v8, v4
	s_waitcnt lgkmcnt(0)
	v_mov_b32_e32 v9, v6
	v_mov_b32_e32 v6, v5
	v_pk_add_f32 v[4:5], v[8:9], v[6:7]
	s_nop 0
	v_add_f32_e32 v3, v4, v5
	v_add_f32_e32 v3, v2, v3
	v_lshl_add_u64 v[4:5], v[0:1], 0, v[166:167]
	global_store_dword v[4:5], v3, off
.LBB0_914:
	s_or_b64 exec, exec, s[36:37]
	s_and_saveexec_b64 s[36:37], s[16:17]
	v_readlane_b32 s41, v251, 62
	s_cbranch_execz .LBB0_923
	ds_read2st64_b32 v[4:5], v194 offset0:8 offset1:88
	ds_read2st64_b32 v[6:7], v194 offset0:168 offset1:248
	s_waitcnt lgkmcnt(1)
	v_mov_b32_e32 v8, v4
	s_waitcnt lgkmcnt(0)
	v_mov_b32_e32 v9, v6
	v_mov_b32_e32 v6, v5
	v_pk_add_f32 v[4:5], v[8:9], v[6:7]
	s_nop 0
	v_add_f32_e32 v3, v4, v5
	v_add_f32_e32 v3, v2, v3
	v_lshl_add_u64 v[4:5], v[0:1], 0, v[168:169]
	global_store_dword v[4:5], v3, off
	s_or_b64 exec, exec, s[36:37]
	s_and_saveexec_b64 s[36:37], s[18:19]
	s_cbranch_execnz .LBB0_924
